# prompt attention: double-buffered LDS tiles (one barrier per tile), permlane cross-row max, trimmed softmax
# speedup vs baseline: 1.0157x; 1.0022x over previous
.LBB0_1760:
	s_bitcmp1_b32 s21, 0
	s_cselect_b32 s84, 0x6000, 0
	s_add_i32 s85, s84, 0x3000
	s_cmp_lg_u32 s21, 0
	s_cbranch_scc1 .Lpa_nobar
	s_barrier
.Lpa_nobar:
	s_and_saveexec_b64 s[18:19], s[0:1]
	s_cbranch_execz .LBB0_1762
	v_add3_u32 v44, v99, v100, s84
	s_waitcnt vmcnt(1)
	ds_write_b128 v44, v[8:11]
.LBB0_1762:
	s_or_b64 exec, exec, s[18:19]
	s_and_saveexec_b64 s[18:19], s[2:3]
	s_cbranch_execz .LBB0_1764
	v_add3_u32 v44, v101, v102, s84
	s_waitcnt vmcnt(1)
	ds_write_b128 v44, v[12:15]
.LBB0_1764:
	s_or_b64 exec, exec, s[18:19]
	s_waitcnt vmcnt(0)
	v_add_u32_e32 v44, s84, v98
	ds_write_b64 v44, v[24:25] offset:13312
	ds_write_b64 v44, v[26:27] offset:13328
	s_waitcnt lgkmcnt(0)
	s_barrier
	s_and_saveexec_b64 s[18:19], s[0:1]
	s_cbranch_execz .LBB0_1766
	v_add_u32_e32 v8, s50, v73
	v_mad_i64_i32 v[8:9], s[52:53], v8, s33, v[60:61]
	global_load_dwordx4 v[8:11], v[8:9], off

.LBB0_1768:
	s_or_b64 exec, exec, s[18:19]
	s_add_i32 s28, s50, 64
	v_lshl_add_u64 v[24:25], s[28:29], 1, v[2:3]
	global_load_dwordx4 v[24:27], v[24:25], off
	s_cmp_gt_i32 s21, s49
	s_cbranch_scc1 .LBB0_1772
	v_add3_u32 v128, v75, v77, s84
	ds_read_b128 v[44:47], v128
	ds_read_b128 v[48:51], v128 offset:64
	ds_read_b128 v[52:55], v128 offset:128
	ds_read_b128 v[56:59], v128 offset:3328
	ds_read_b128 v[64:67], v128 offset:3392
	ds_read_b128 v[68:71], v128 offset:3456
	ds_read_b128 v[108:111], v128 offset:6656
	ds_read_b128 v[112:115], v128 offset:6720
	ds_read_b128 v[116:119], v128 offset:6784
	ds_read_b128 v[120:123], v128 offset:9984
	ds_read_b128 v[124:127], v128 offset:10048
	ds_read_b128 v[132:135], v128 offset:10112
	s_waitcnt lgkmcnt(11)
	v_mfma_f32_16x16x32_bf16 v[44:47], v[44:47], v[4:7], 0
	s_add_i32 s18, s50, 63
	s_cmp_le_i32 s18, s30
	s_waitcnt lgkmcnt(8)
	v_mfma_f32_16x16x32_bf16 v[56:59], v[56:59], v[4:7], 0
	s_waitcnt lgkmcnt(5)
	v_mfma_f32_16x16x32_bf16 v[108:111], v[108:111], v[4:7], 0
	s_waitcnt lgkmcnt(2)
	v_mfma_f32_16x16x32_bf16 v[120:123], v[120:123], v[4:7], 0
	v_mfma_f32_16x16x32_bf16 v[44:47], v[48:51], v[20:23], v[44:47]
	v_mfma_f32_16x16x32_bf16 v[48:51], v[64:67], v[20:23], v[56:59]
	v_mfma_f32_16x16x32_bf16 v[64:67], v[112:115], v[20:23], v[108:111]
	s_waitcnt lgkmcnt(1)
	v_mfma_f32_16x16x32_bf16 v[108:111], v[124:127], v[20:23], v[120:123]
	v_mfma_f32_16x16x32_bf16 v[56:59], v[52:55], v[16:19], v[44:47]
	v_mfma_f32_16x16x32_bf16 v[52:55], v[68:71], v[16:19], v[48:51]
	v_mfma_f32_16x16x32_bf16 v[48:51], v[116:119], v[16:19], v[64:67]
	s_waitcnt lgkmcnt(0)
	v_mfma_f32_16x16x32_bf16 v[44:47], v[132:135], v[16:19], v[108:111]
	s_cbranch_scc1 .LBB0_1771
	v_add_u32_e32 v64, s50, v74
	v_cmp_gt_i32_e32 vcc, v64, v106
	s_nop 1
	v_cndmask_b32_e32 v65, v56, v236, vcc
	v_cmp_lt_i32_e32 vcc, v64, v106
	s_nop 1
	v_cndmask_b32_e32 v56, v65, v56, vcc
	v_add_u32_e32 v65, 2, v64
	v_cndmask_b32_e32 v57, v236, v57, vcc
	v_cmp_le_i32_e32 vcc, v65, v106
	v_add_u32_e32 v65, 3, v64
	s_nop 0
	v_cndmask_b32_e32 v58, v236, v58, vcc
	v_cmp_le_i32_e32 vcc, v65, v106
	v_add_u32_e32 v65, 16, v64
	s_nop 0
	v_cndmask_b32_e32 v59, v236, v59, vcc
	v_cmp_le_i32_e32 vcc, v65, v106
	v_add_u32_e32 v65, 17, v64
	s_nop 0
	v_cndmask_b32_e32 v52, v236, v52, vcc
	v_cmp_le_i32_e32 vcc, v65, v106
	v_add_u32_e32 v65, 18, v64
	s_nop 0
	v_cndmask_b32_e32 v53, v236, v53, vcc
	v_cmp_le_i32_e32 vcc, v65, v106
	v_add_u32_e32 v65, 19, v64
	s_nop 0
	v_cndmask_b32_e32 v54, v236, v54, vcc
	v_cmp_le_i32_e32 vcc, v65, v106
	v_add_u32_e32 v65, 32, v64
	s_nop 0
	v_cndmask_b32_e32 v55, v236, v55, vcc
	v_cmp_le_i32_e32 vcc, v65, v106
	v_add_u32_e32 v65, 33, v64
	s_nop 0
	v_cndmask_b32_e32 v48, v236, v48, vcc
	v_cmp_le_i32_e32 vcc, v65, v106
	v_add_u32_e32 v65, 34, v64
	s_nop 0
	v_cndmask_b32_e32 v49, v236, v49, vcc
	v_cmp_le_i32_e32 vcc, v65, v106
	v_add_u32_e32 v65, 35, v64
	s_nop 0
	v_cndmask_b32_e32 v50, v236, v50, vcc
	v_cmp_le_i32_e32 vcc, v65, v106
	v_add_u32_e32 v65, 48, v64
	s_nop 0
	v_cndmask_b32_e32 v51, v236, v51, vcc
	v_cmp_le_i32_e32 vcc, v65, v106
	v_add_u32_e32 v65, 49, v64
	s_nop 0
	v_cndmask_b32_e32 v44, v236, v44, vcc
	v_cmp_le_i32_e32 vcc, v65, v106
	v_add_u32_e32 v65, 50, v64
	v_add_u32_e32 v64, 51, v64
	v_cndmask_b32_e32 v45, v236, v45, vcc
	v_cmp_le_i32_e32 vcc, v65, v106
	s_nop 1
	v_cndmask_b32_e32 v46, v236, v46, vcc
	v_cmp_le_i32_e32 vcc, v64, v106
	s_nop 1
	v_cndmask_b32_e32 v47, v236, v47, vcc
.LBB0_1771:
	s_nop 3
	v_max3_f32 v64, v56, v57, v58
	v_max3_f32 v64, v64, v59, v52
	v_max3_f32 v64, v64, v53, v54
	v_max3_f32 v64, v64, v55, v48
	v_max3_f32 v64, v64, v49, v50
	v_max3_f32 v64, v64, v51, v44
	v_max3_f32 v64, v64, v45, v46
	v_max3_f32 v64, v64, v47, s76
	v_mov_b32_e32 v65, v64
	v_add_u32_e32 v114, s85, v94
	v_add_u32_e32 v115, s85, v95
	v_permlane16_swap_b32_e32 v64, v65
	v_add_u32_e32 v116, s85, v96
	v_add_u32_e32 v117, s85, v97
	v_max_f32_e32 v64, v64, v65
	v_mov_b32_e32 v65, v64
	s_nop 1
	v_permlane32_swap_b32_e32 v64, v65
	v_max3_f32 v69, v107, v64, v65
	v_sub_f32_e32 v64, v107, v69
	v_pk_add_f32 v[56:57], v[56:57], v[68:69] op_sel:[0,1] op_sel_hi:[1,1] neg_lo:[0,1] neg_hi:[0,1]
	v_pk_add_f32 v[58:59], v[58:59], v[68:69] op_sel:[0,1] op_sel_hi:[1,1] neg_lo:[0,1] neg_hi:[0,1]
	v_pk_add_f32 v[52:53], v[52:53], v[68:69] op_sel:[0,1] op_sel_hi:[1,1] neg_lo:[0,1] neg_hi:[0,1]
	v_pk_add_f32 v[54:55], v[54:55], v[68:69] op_sel:[0,1] op_sel_hi:[1,1] neg_lo:[0,1] neg_hi:[0,1]
	v_pk_add_f32 v[48:49], v[48:49], v[68:69] op_sel:[0,1] op_sel_hi:[1,1] neg_lo:[0,1] neg_hi:[0,1]
	v_pk_add_f32 v[50:51], v[50:51], v[68:69] op_sel:[0,1] op_sel_hi:[1,1] neg_lo:[0,1] neg_hi:[0,1]
	v_pk_add_f32 v[44:45], v[44:45], v[68:69] op_sel:[0,1] op_sel_hi:[1,1] neg_lo:[0,1] neg_hi:[0,1]
	v_pk_add_f32 v[46:47], v[46:47], v[68:69] op_sel:[0,1] op_sel_hi:[1,1] neg_lo:[0,1] neg_hi:[0,1]
	v_exp_f32_e32 v56, v56
	v_exp_f32_e32 v57, v57
	v_exp_f32_e32 v58, v58
	v_exp_f32_e32 v59, v59
	v_exp_f32_e32 v52, v52
	v_exp_f32_e32 v53, v53
	v_exp_f32_e32 v54, v54
	v_exp_f32_e32 v55, v55
	v_exp_f32_e32 v70, v48
	v_exp_f32_e32 v71, v49
	v_exp_f32_e32 v107, v50
	v_exp_f32_e32 v108, v51
	v_exp_f32_e32 v109, v44
	v_exp_f32_e32 v110, v45
	v_exp_f32_e32 v111, v46
	v_exp_f32_e32 v112, v47
	v_exp_f32_e32 v68, v64
	v_add_f32_e32 v65, v56, v57
	v_add_f32_e32 v65, v58, v65
	v_add_f32_e32 v65, v59, v65
	v_add_f32_e32 v65, v52, v65
	v_add_f32_e32 v65, v53, v65
	v_add_f32_e32 v65, v54, v65
	v_add_f32_e32 v65, v55, v65
	v_add_f32_e32 v48, v70, v65
	v_add_f32_e32 v48, v71, v48
	v_add_f32_e32 v48, v107, v48
	v_add_f32_e32 v48, v108, v48
	v_add_f32_e32 v44, v109, v48
	v_add_f32_e32 v44, v110, v44
	v_add_f32_e32 v44, v111, v44
	v_add_f32_e32 v113, v112, v44
	v_cvt_pk_bf16_f32 v44, v56, v57
	v_cvt_pk_bf16_f32 v45, v58, v59
	v_cvt_pk_bf16_f32 v46, v52, v53
	v_cvt_pk_bf16_f32 v47, v54, v55
	ds_read_b128 v[48:51], v114 offset:1024
	ds_read_b128 v[52:55], v115 offset:1024
	ds_read_b128 v[56:59], v116 offset:1024
	ds_read_b128 v[64:67], v117 offset:1024
	v_pk_mul_f32 v[38:39], v[38:39], v[68:69] op_sel_hi:[1,0]
	v_pk_mul_f32 v[36:37], v[36:37], v[68:69] op_sel_hi:[1,0]
	v_pk_mul_f32 v[34:35], v[34:35], v[68:69] op_sel_hi:[1,0]
	v_pk_mul_f32 v[32:33], v[32:33], v[68:69] op_sel_hi:[1,0]
	v_pk_mul_f32 v[30:31], v[30:31], v[68:69] op_sel_hi:[1,0]
	v_pk_mul_f32 v[28:29], v[28:29], v[68:69] op_sel_hi:[1,0]
	v_pk_mul_f32 v[42:43], v[42:43], v[68:69] op_sel_hi:[1,0]
	v_pk_mul_f32 v[40:41], v[40:41], v[68:69] op_sel_hi:[1,0]
	s_waitcnt lgkmcnt(3)
	v_mfma_f32_16x16x32_bf16 v[36:39], v[48:51], v[44:47], v[36:39]
	s_waitcnt lgkmcnt(2)
	v_mfma_f32_16x16x32_bf16 v[32:35], v[52:55], v[44:47], v[32:35]
	s_waitcnt lgkmcnt(1)
	v_mfma_f32_16x16x32_bf16 v[28:31], v[56:59], v[44:47], v[28:31]
	s_waitcnt lgkmcnt(0)
	v_mfma_f32_16x16x32_bf16 v[40:43], v[64:67], v[44:47], v[40:43]
	ds_read_b128 v[48:51], v114 offset:1088
	ds_read_b128 v[52:55], v115 offset:1088
	ds_read_b128 v[56:59], v116 offset:1088
	ds_read_b128 v[64:67], v117 offset:1088
	v_cvt_pk_bf16_f32 v44, v70, v71
	v_cvt_pk_bf16_f32 v45, v107, v108
	v_cvt_pk_bf16_f32 v46, v109, v110
	v_cvt_pk_bf16_f32 v47, v111, v112
	s_waitcnt lgkmcnt(3)
	v_mfma_f32_16x16x32_bf16 v[36:39], v[48:51], v[44:47], v[36:39]
	v_fmac_f32_e32 v113, v0, v68
	v_mov_b32_e32 v107, v69
	v_mov_b32_e32 v0, v113
	s_waitcnt lgkmcnt(2)
	v_mfma_f32_16x16x32_bf16 v[32:35], v[52:55], v[44:47], v[32:35]
	s_waitcnt lgkmcnt(1)
	v_mfma_f32_16x16x32_bf16 v[28:31], v[56:59], v[44:47], v[28:31]
	s_waitcnt lgkmcnt(0)
	v_mfma_f32_16x16x32_bf16 v[40:43], v[64:67], v[44:47], v[40:43]
